# v66 + latent attention units permuted so the 16 units sharing one K/V set run on one XCD (u = rotl8(wgid,5))
# speedup vs baseline: 1.0052x; 1.0052x over previous
.LBB0_345:
	s_or_b64 exec, exec, s[2:3]
	s_waitcnt vmcnt(0) lgkmcnt(0)
	s_barrier
	ds_read_b32 v0, v161 offset:8
	s_mov_b64 s[2:3], -1
	s_waitcnt lgkmcnt(0)
	s_barrier
	v_cmp_le_i32_e32 vcc, s8, v0
	v_readfirstlane_b32 s4, v0
	v_readlane_b32 s101, v252, 8
	s_lshr_b32 s100, s101, 5
	s_lshl_b32 s100, s100, 2
	s_bfe_u32 s101, s101, 0x20001
	s_or_b32 s100, s100, s101
	s_addk_i32 s100, 0x200
	v_readlane_b32 s101, v252, 8
	s_and_b32 s101, s101, 0x19
	s_cmp_eq_u32 s101, 0
	s_cselect_b32 s100, s100, 0x7fffffff
	s_cmpk_lt_u32 s4, 0x200
	s_cselect_b32 s100, s100, 0x7fffffff
	v_readlane_b32 s101, v252, 8
	s_mul_i32 s101, s101, 0x101
	s_bfe_u32 s101, s101, 0x80003
	s_addk_i32 s101, 0x100
	s_cmpk_lt_u32 s4, 0x100
	s_cselect_b32 s100, s101, s100
	s_cbranch_vccnz .LBB0_340
	s_cmpk_gt_i32 s4, 0xff
	s_cbranch_scc0 .LBB0_372
	s_cmpk_gt_u32 s4, 0x1ff
	s_cbranch_scc0 .LBB0_359
	s_add_i32 s2, s4, 0xfffffe00
	s_lshr_b32 s6, s2, 2
	s_lshl_b32 s11, s6, 8
	v_mov_b32_e32 v10, v236
	s_add_i32 s2, s11, 0x4000
	v_readlane_b32 s0, v255, 11
	v_and_b32_e32 v64, 31, v10
	v_ashrrev_i32_e32 v0, 1, v10
	v_and_b32_e32 v0, 0xffffffe0, v0
	v_or_b32_e32 v1, s2, v64
	v_readlane_b32 s1, v255, 12
	v_add_u32_e32 v206, v1, v0
	s_movk_i32 s12, 0x1200
	v_mov_b64_e32 v[0:1], s[0:1]
	v_mad_i64_i32 v[0:1], s[2:3], v206, s12, v[0:1]
	s_and_b32 s7, s4, 3
	s_lshl_b32 s3, s4, 5
	s_lshl_b32 s5, s7, 7
	s_lshl_b32 s64, s7, 8
	v_ashrrev_i32_e32 v50, 3, v10
	s_lshl_b32 s2, s6, 7
	s_and_b32 s7, s3, 64
	v_lshl_add_u64 v[8:9], v[0:1], 0, s[64:65]
	s_or_b32 s64, s7, s2
	v_ashrrev_i32_e32 v51, 31, v50
	v_lshl_add_u64 v[48:49], v[50:51], 0, s[64:65]
	v_mov_b64_e32 v[0:1], s[28:29]
	v_mad_u64_u32 v[0:1], s[2:3], v48, s12, v[0:1]
	s_lshl_b32 s2, s7, 1
	s_add_u32 s2, s9, s2
	s_addc_u32 s3, s10, 0
	s_lshl_b32 s6, s6, 11
	s_or_b32 s7, s11, 0x3800
	v_lshlrev_b32_e32 v2, 4, v10
	v_mov_b32_e32 v56, s7
	v_mov_b32_e32 v57, s6
	v_cmp_gt_i32_e32 vcc, 0, v50
	v_and_b32_e32 v208, 0x70, v2
	v_mov_b32_e32 v209, v161
	v_cndmask_b32_e32 v2, v56, v57, vcc
	s_movk_i32 s16, 0x800
	v_lshl_add_u64 v[210:211], s[2:3], 0, v[208:209]
	v_add3_u32 v2, v50, v2, s16
	v_mad_i32_i24 v1, v49, s12, v1
	v_mad_i64_i32 v[2:3], s[2:3], v2, s12, v[210:211]
	v_lshl_add_u64 v[0:1], v[0:1], 0, v[208:209]
	s_movk_i32 s2, 0x1000
	v_add_co_u32_e32 v54, vcc, s2, v0
	v_bfe_u32 v52, v10, 5, 1
	s_nop 0
	v_addc_co_u32_e32 v55, vcc, 0, v1, vcc
	global_load_dwordx4 v[0:3], v[2:3], off
	s_nop 0
	global_load_dwordx4 v[4:7], v[54:55], off
	v_lshlrev_b32_e32 v212, 4, v52
	v_mov_b32_e32 v213, v161
	v_lshl_add_u64 v[8:9], v[8:9], 0, v[212:213]
	global_load_dwordx4 v[162:165], v[8:9], off offset:512
	global_load_dwordx4 v[166:169], v[8:9], off offset:640
	global_load_dwordx4 v[170:173], v[8:9], off offset:544
	global_load_dwordx4 v[174:177], v[8:9], off offset:672
	global_load_dwordx4 v[178:181], v[8:9], off offset:576
	global_load_dwordx4 v[182:185], v[8:9], off offset:608
	global_load_dwordx4 v[186:189], v[8:9], off offset:704
	global_load_dwordx4 v[190:193], v[8:9], off offset:736
	s_movk_i32 s2, 0x90
	v_mul_lo_u32 v202, v50, s2
	v_and_b32_e32 v120, -8, v10
	v_mad_u32_u24 v65, v64, s2, 16
	v_add3_u32 v10, 16, v202, v208
	v_add_u32_e32 v53, v65, v212
	v_sub_u32_e32 v11, v10, v120
	v_add_u32_e32 v11, 0x2400, v11
	s_movk_i32 s2, 0x88
	v_lshlrev_b32_e32 v214, 3, v52
	v_mul_lo_u32 v203, v50, s2
	v_mul_u32_u24_e32 v209, 0x90, v64
	v_mul_u32_u24_e32 v213, 0x88, v64
	v_readlane_b32 s0, v255, 24
	v_readlane_b32 s1, v255, 25
	s_mov_b32 s11, 1
	v_ashrrev_i32_e32 v207, 31, v206
	s_mov_b32 s17, 0x41000000
	s_waitcnt vmcnt(9)
	ds_write_b128 v10, v[0:3]
	s_waitcnt vmcnt(8)
	ds_write2_b64 v11, v[4:5], v[6:7] offset1:1
	s_waitcnt lgkmcnt(0)
	s_barrier
	ds_read_b128 v[0:3], v53
	ds_read_b128 v[4:7], v53 offset:32
	ds_read_b128 v[8:11], v53 offset:4608
	ds_read_b128 v[12:15], v53 offset:4640
	s_waitcnt vmcnt(7) lgkmcnt(3)
	v_mfma_f32_32x32x16_bf16 v[16:31], v[0:3], v[162:165], 0
	s_waitcnt lgkmcnt(1)
	v_mfma_f32_32x32x16_bf16 v[32:47], v[8:11], v[162:165], 0
	s_waitcnt vmcnt(6)
	v_mfma_f32_32x32x16_bf16 v[88:103], v[0:3], v[166:169], 0
	v_mfma_f32_32x32x16_bf16 v[72:87], v[8:11], v[166:169], 0
	s_waitcnt vmcnt(5)
	v_mfma_f32_32x32x16_bf16 v[16:31], v[4:7], v[170:173], v[16:31]
	s_waitcnt lgkmcnt(0)
	v_mfma_f32_32x32x16_bf16 v[32:47], v[12:15], v[170:173], v[32:47]
	s_waitcnt vmcnt(4)
	v_mfma_f32_32x32x16_bf16 v[88:103], v[4:7], v[174:177], v[88:103]
	ds_read_b128 v[0:3], v53 offset:64
	ds_read_b128 v[4:7], v53 offset:96
	v_mfma_f32_32x32x16_bf16 v[72:87], v[12:15], v[174:177], v[72:87]
	ds_read_b128 v[8:11], v53 offset:4672
	ds_read_b128 v[12:15], v53 offset:4704
	v_mad_u64_u32 v[52:53], s[2:3], v48, s12, 0
	s_movk_i32 s2, 0xffc0
	s_nop 0
	v_cmp_gt_i32_e32 vcc, s2, v50
	s_movk_i32 s2, 0x840
	v_mad_i32_i24 v53, v49, s12, v53
	s_waitcnt vmcnt(3) lgkmcnt(3)
	v_mfma_f32_32x32x16_bf16 v[16:31], v[0:3], v[178:181], v[16:31]
	v_or_b32_e32 v52, v52, v208
	v_lshl_add_u64 v[218:219], s[0:1], 0, v[52:53]
	s_waitcnt lgkmcnt(1)
	v_mfma_f32_32x32x16_bf16 v[32:47], v[8:11], v[178:181], v[32:47]
	s_waitcnt vmcnt(2)
	v_mfma_f32_32x32x16_bf16 v[16:31], v[4:7], v[182:185], v[16:31]
	s_waitcnt vmcnt(1)
	v_mfma_f32_32x32x16_bf16 v[88:103], v[0:3], v[186:189], v[88:103]
	s_nop 9
	v_max_f32_e32 v2, v17, v17
	v_max_f32_e32 v3, v16, v16
	v_max_f32_e32 v2, v3, v2
	v_cndmask_b32_e32 v0, v56, v57, vcc
	v_add3_u32 v0, v50, v0, s2
	v_mad_i64_i32 v[0:1], s[2:3], v0, s12, v[210:211]
	s_waitcnt lgkmcnt(0)
	v_mfma_f32_32x32x16_bf16 v[32:47], v[12:15], v[182:185], v[32:47]
	global_load_dwordx4 v[194:197], v[0:1], off
	global_load_dwordx4 v[198:201], v[54:55], off offset:128
	s_mov_b64 s[2:3], 0x880
	v_lshl_add_u64 v[220:221], v[50:51], 0, s[2:3]
	s_waitcnt vmcnt(2)
	v_mfma_f32_32x32x16_bf16 v[88:103], v[4:7], v[190:193], v[88:103]
	s_nop 5
	v_max3_f32 v4, v18, v19, v33
	v_max3_f32 v2, v2, v32, v34
	v_max3_f32 v3, v4, v22, v23
	v_max3_f32 v2, v2, v35, v20
	v_max3_f32 v3, v3, v38, v39
	v_max3_f32 v2, v2, v21, v36
	v_max3_f32 v3, v3, v26, v27
	v_max3_f32 v2, v2, v37, v24
	v_max3_f32 v3, v3, v42, v43
	v_max3_f32 v2, v2, v25, v40
	v_max3_f32 v3, v3, v30, v31
	v_max3_f32 v2, v2, v41, v28
	v_max3_f32 v3, v3, v46, v47
	v_max3_f32 v2, v2, v29, v44
	v_max3_f32 v2, v2, v45, v3
	v_mov_b32_e32 v3, v2
	s_nop 1
	v_permlane32_swap_b32_e32 v2, v3
	v_max_f32_e32 v3, v3, v3
	v_max_f32_e32 v2, v2, v2
	v_max_f32_e32 v48, v2, v3
	v_sub_f32_e32 v16, v16, v48
	v_sub_f32_e32 v17, v17, v48
	v_sub_f32_e32 v49, v32, v48
	v_sub_f32_e32 v54, v33, v48
	v_exp_f32_e32 v32, v16
	v_exp_f32_e32 v33, v17
	v_sub_f32_e32 v18, v18, v48
	v_sub_f32_e32 v19, v19, v48
	v_exp_f32_e32 v60, v49
	v_exp_f32_e32 v61, v54
	v_sub_f32_e32 v55, v34, v48
	v_sub_f32_e32 v56, v35, v48
	v_exp_f32_e32 v34, v18
	v_exp_f32_e32 v35, v19
	v_sub_f32_e32 v20, v20, v48
	v_sub_f32_e32 v21, v21, v48
	v_exp_f32_e32 v106, v55
	v_exp_f32_e32 v107, v56
	v_sub_f32_e32 v57, v36, v48
	v_sub_f32_e32 v58, v37, v48
	v_pk_add_f32 v[16:17], v[32:33], 0 op_sel_hi:[1,0]
	v_exp_f32_e32 v36, v20
	v_exp_f32_e32 v37, v21
	v_sub_f32_e32 v22, v22, v48
	v_sub_f32_e32 v23, v23, v48
	v_pk_add_f32 v[16:17], v[60:61], v[16:17]
	v_exp_f32_e32 v108, v57
	v_exp_f32_e32 v109, v58
	v_sub_f32_e32 v59, v38, v48
	v_sub_f32_e32 v62, v39, v48
	v_pk_add_f32 v[16:17], v[34:35], v[16:17]
	v_exp_f32_e32 v38, v22
	v_exp_f32_e32 v39, v23
	v_mfma_f32_32x32x16_bf16 v[72:87], v[8:11], v[186:189], v[72:87]
	v_sub_f32_e32 v24, v24, v48
	v_sub_f32_e32 v25, v25, v48
	v_add_f32_e64 v16, v106, v16
	v_add_f32_e64 v17, v107, v17
	v_exp_f32_e32 v110, v59
	v_exp_f32_e32 v111, v62
	v_sub_f32_e32 v40, v40, v48
	v_sub_f32_e32 v41, v41, v48
	v_pk_add_f32 v[16:17], v[36:37], v[16:17]
	v_exp_f32_e32 v112, v24
	v_exp_f32_e32 v113, v25
	v_sub_f32_e32 v26, v26, v48
	v_sub_f32_e32 v27, v27, v48
	v_pk_add_f32 v[16:17], v[108:109], v[16:17]
	v_exp_f32_e32 v54, v40
	v_exp_f32_e32 v55, v41
	v_sub_f32_e32 v42, v42, v48
	v_sub_f32_e32 v43, v43, v48
	v_pk_add_f32 v[16:17], v[38:39], v[16:17]
	v_exp_f32_e32 v114, v26
	v_exp_f32_e32 v115, v27
	v_sub_f32_e32 v28, v28, v48
	v_sub_f32_e32 v29, v29, v48
	v_pk_add_f32 v[16:17], v[110:111], v[16:17]
	v_exp_f32_e32 v56, v42
	v_exp_f32_e32 v57, v43
	v_sub_f32_e32 v44, v44, v48
	v_sub_f32_e32 v45, v45, v48
	v_pk_add_f32 v[16:17], v[112:113], v[16:17]
	v_exp_f32_e32 v116, v28
	v_exp_f32_e32 v117, v29
	v_sub_f32_e32 v30, v30, v48
	v_sub_f32_e32 v31, v31, v48
	v_pk_add_f32 v[16:17], v[54:55], v[16:17]
	v_exp_f32_e32 v58, v44
	v_exp_f32_e32 v59, v45
	v_sub_f32_e32 v46, v46, v48
	v_sub_f32_e32 v47, v47, v48
	v_pk_add_f32 v[16:17], v[114:115], v[16:17]
	v_exp_f32_e32 v118, v30
	v_exp_f32_e32 v119, v31
	v_mfma_f32_32x32x16_bf16 v[72:87], v[12:15], v[190:193], v[72:87]
	v_add_f32_e64 v16, v56, v16
	v_add_f32_e64 v17, v57, v17
	v_exp_f32_e32 v62, v46
	v_exp_f32_e32 v63, v47
	v_pk_add_f32 v[16:17], v[116:117], v[16:17]
	v_max_f32_e32 v18, v88, v88
	v_pk_add_f32 v[16:17], v[58:59], v[16:17]
	v_lshlrev_b32_e32 v44, 3, v64
	v_pk_add_f32 v[16:17], v[118:119], v[16:17]
	v_sub_u32_e32 v44, v65, v44
	v_pk_add_f32 v[16:17], v[62:63], v[16:17]
	v_add_u32_e32 v44, v44, v214
	v_pk_add_f32 v[16:17], v[16:17], v[16:17] op_sel_hi:[0,1]
	v_max_f32_e32 v16, v89, v89
	v_max_f32_e32 v16, v18, v16
	v_max3_f32 v18, v90, v91, v73
	v_max3_f32 v16, v16, v72, v74
	v_max3_f32 v16, v16, v75, v92
	v_max3_f32 v18, v18, v94, v95
	v_max3_f32 v16, v16, v93, v76
	v_max3_f32 v18, v18, v78, v79
	v_max3_f32 v16, v16, v77, v96
	v_max3_f32 v18, v18, v98, v99
	v_max3_f32 v16, v16, v97, v80
	v_max3_f32 v18, v18, v82, v83
	v_max3_f32 v16, v16, v81, v100
	v_max3_f32 v18, v18, v102, v103
	v_max3_f32 v16, v16, v101, v84
	v_max3_f32 v18, v18, v86, v87
	v_max3_f32 v16, v16, v85, v18
	v_mov_b32_e32 v18, v16
	s_nop 1
	v_permlane32_swap_b32_e32 v16, v18
	v_max_f32_e32 v18, v18, v18
	v_max_f32_e32 v16, v16, v16
	v_max_f32_e32 v104, v16, v18
	v_add_u32_e32 v140, 0x2000, v44
	v_add_u32_e32 v141, 0x3000, v44
	v_sub_f32_e32 v40, v88, v104
	v_sub_f32_e32 v41, v89, v104
	v_sub_f32_e32 v42, v90, v104
	v_sub_f32_e32 v43, v91, v104
	ds_read2_b64 v[88:91], v140 offset0:128 offset1:130
	ds_read2_b64 v[122:125], v141 offset0:160 offset1:162
	v_exp_f32_e64 v2, -v48
	v_exp_f32_e64 v18, -v104
	v_sub_f32_e32 v45, v92, v104
	v_sub_f32_e32 v46, v93, v104
	v_cvt_pk_bf16_f32 v32, v32, v33
	v_cvt_pk_bf16_f32 v33, v34, v35
	v_cvt_pk_bf16_f32 v34, v36, v37
	v_sub_f32_e32 v36, v94, v104
	v_sub_f32_e32 v37, v95, v104
	v_exp_f32_e32 v126, v40
	v_exp_f32_e32 v127, v41
	v_exp_f32_e32 v128, v42
	v_exp_f32_e32 v129, v43
	v_exp_f32_e32 v130, v45
	v_exp_f32_e32 v131, v46
	v_exp_f32_e32 v132, v36
	v_exp_f32_e32 v133, v37
	v_mul_f32_e32 v0, 0, v2
	v_mov_b32_e32 v49, v0
	v_mov_b32_e32 v16, v161
	v_pk_add_f32 v[216:217], v[48:49], v[16:17]
	v_mul_f32_e32 v16, 0, v18
	v_mov_b32_e32 v1, v0
	v_mov_b32_e32 v2, v0
	v_mov_b32_e32 v3, v0
	v_mov_b32_e32 v4, v0
	v_mov_b32_e32 v5, v0
	v_mov_b32_e32 v6, v0
	v_mov_b32_e32 v7, v0
	v_mov_b32_e32 v8, v0
	v_mov_b32_e32 v9, v0
	v_mov_b32_e32 v10, v0
	v_mov_b32_e32 v11, v0
	v_mov_b32_e32 v12, v0
	v_mov_b32_e32 v13, v0
	v_mov_b32_e32 v14, v0
	v_mov_b32_e32 v15, v0
	v_pk_add_f32 v[48:49], v[216:217], 0 neg_lo:[1,1] neg_hi:[1,1]
	v_mov_b32_e32 v17, v16
	v_mov_b32_e32 v18, v16
	v_mov_b32_e32 v19, v16
	v_mov_b32_e32 v20, v16
	v_mov_b32_e32 v21, v16
	v_mov_b32_e32 v22, v16
	v_mov_b32_e32 v23, v16
	v_mov_b32_e32 v24, v16
	v_mov_b32_e32 v25, v16
	v_mov_b32_e32 v26, v16
	v_mov_b32_e32 v27, v16
	v_mov_b32_e32 v28, v16
	v_mov_b32_e32 v29, v16
	v_mov_b32_e32 v30, v16
	v_mov_b32_e32 v31, v16
	v_cvt_pk_bf16_f32 v35, v38, v39
	v_cvt_pk_bf16_f32 v92, v126, v127
	v_cvt_pk_bf16_f32 v93, v128, v129
	v_cvt_pk_bf16_f32 v94, v130, v131
	v_cvt_pk_bf16_f32 v95, v132, v133
	v_sub_f32_e32 v49, v72, v104
	v_sub_f32_e32 v121, v73, v104
	v_sub_f32_e32 v134, v74, v104
	v_sub_f32_e32 v135, v75, v104
	v_sub_f32_e32 v136, v76, v104
	v_sub_f32_e32 v137, v77, v104
	v_sub_f32_e32 v138, v78, v104
	v_sub_f32_e32 v139, v79, v104
	s_waitcnt lgkmcnt(1)
	v_mfma_f32_32x32x16_bf16 v[64:79], v[88:91], v[32:35], v[0:15]
	v_sub_f32_e32 v142, v80, v104
	v_sub_f32_e32 v80, v96, v104
	v_sub_f32_e32 v143, v97, v104
	v_sub_f32_e32 v144, v98, v104
	v_sub_f32_e32 v145, v99, v104
	ds_read2_b64 v[96:99], v141 offset0:164 offset1:166
	v_mov_b32_e32 v105, v16
	s_waitcnt lgkmcnt(1)
	v_mfma_f32_32x32x16_bf16 v[0:15], v[122:125], v[32:35], v[0:15]
	v_cvt_pk_bf16_f32 v54, v54, v55
	v_cvt_pk_bf16_f32 v55, v56, v57
	v_cvt_pk_bf16_f32 v56, v58, v59
	v_cvt_pk_bf16_f32 v57, v62, v63
	v_mov_b32_e32 v50, v48
	v_mov_b32_e32 v51, v48
	v_mov_b32_e32 v52, v48
	v_mfma_f32_32x32x16_bf16 v[32:47], v[88:91], v[92:95], v[16:31]
	ds_read2_b64 v[88:91], v140 offset0:132 offset1:134
	v_mov_b32_e32 v53, v48
	v_mfma_f32_32x32x16_bf16 v[16:31], v[122:125], v[92:95], v[16:31]
	v_sub_f32_e32 v122, v100, v104
	v_sub_f32_e32 v123, v101, v104
	v_cvt_pk_bf16_f32 v93, v114, v115
	v_sub_f32_e32 v114, v102, v104
	v_sub_f32_e32 v115, v103, v104
	v_cvt_pk_bf16_f32 v92, v112, v113
	v_exp_f32_e32 v100, v80
	v_exp_f32_e32 v101, v143
	v_exp_f32_e32 v102, v144
	v_exp_f32_e32 v103, v145
	v_exp_f32_e32 v112, v122
	v_exp_f32_e32 v113, v123
	v_exp_f32_e32 v114, v114
	v_exp_f32_e32 v115, v115
	v_cvt_pk_bf16_f32 v94, v116, v117
	v_cvt_pk_bf16_f32 v95, v118, v119
	v_sub_f32_e32 v116, v81, v104
	v_sub_f32_e32 v117, v82, v104
	s_waitcnt lgkmcnt(0)
	v_mfma_f32_32x32x16_bf16 v[64:79], v[88:91], v[92:95], v[64:79]
	v_sub_f32_e32 v118, v83, v104
	ds_read2_b64 v[80:83], v140 offset0:136 offset1:138
	v_sub_f32_e32 v119, v84, v104
	v_sub_f32_e32 v122, v85, v104
	v_exp_f32_e32 v84, v49
	v_exp_f32_e32 v85, v121
	v_sub_f32_e32 v123, v86, v104
	v_mfma_f32_32x32x16_bf16 v[0:15], v[96:99], v[92:95], v[0:15]
	v_cvt_pk_bf16_f32 v92, v100, v101
	v_cvt_pk_bf16_f32 v93, v102, v103
	v_cvt_pk_bf16_f32 v94, v112, v113
	v_cvt_pk_bf16_f32 v95, v114, v115
	v_sub_f32_e32 v49, v87, v104
	s_nop 0
	v_mfma_f32_32x32x16_bf16 v[32:47], v[88:91], v[92:95], v[32:47]
	v_cvt_pk_bf16_f32 v88, v60, v61
	v_add_f32_e64 v60, v126, 0
	v_add_f32_e64 v61, v127, 0
	v_cvt_pk_bf16_f32 v89, v106, v107
	v_cvt_pk_bf16_f32 v90, v108, v109
	v_cvt_pk_bf16_f32 v91, v110, v111
	v_pk_add_f32 v[60:61], v[84:85], v[60:61]
	v_cvt_pk_bf16_f32 v84, v84, v85
	v_mfma_f32_32x32x16_bf16 v[16:31], v[96:99], v[92:95], v[16:31]
	ds_read2_b64 v[92:95], v141 offset0:168 offset1:170
	v_exp_f32_e32 v96, v134
	v_exp_f32_e32 v97, v135
	v_exp_f32_e32 v98, v136
	v_exp_f32_e32 v99, v137
	v_pk_add_f32 v[60:61], v[128:129], v[60:61]
	v_cvt_pk_bf16_f32 v85, v96, v97
	s_waitcnt lgkmcnt(1)
	v_mfma_f32_32x32x16_bf16 v[64:79], v[80:83], v[88:91], v[64:79]
	v_add_f32_e64 v60, v96, v60
	v_add_f32_e64 v61, v97, v61
	v_cvt_pk_bf16_f32 v86, v98, v99
	v_add_f32_e64 v60, v130, v60
	v_add_f32_e64 v61, v131, v61
	v_pk_add_f32 v[60:61], v[98:99], v[60:61]
	s_nop 0
	v_pk_add_f32 v[60:61], v[132:133], v[60:61]
	s_waitcnt lgkmcnt(0)
	v_mfma_f32_32x32x16_bf16 v[0:15], v[92:95], v[88:91], v[0:15]
	v_exp_f32_e32 v88, v138
	v_exp_f32_e32 v89, v139
	v_exp_f32_e32 v90, v142
	v_exp_f32_e32 v91, v116
	v_cvt_pk_bf16_f32 v87, v88, v89
	v_pk_add_f32 v[88:89], v[88:89], v[60:61]
	s_nop 0
	v_mfma_f32_32x32x16_bf16 v[32:47], v[80:83], v[84:87], v[32:47]
	ds_read2_b64 v[80:83], v140 offset0:140 offset1:142
	ds_read2_b64 v[58:61], v141 offset0:172 offset1:174
	v_add_f32_e64 v62, v100, v88
	v_add_f32_e64 v63, v101, v89
	v_exp_f32_e32 v88, v123
	v_exp_f32_e32 v89, v49
	v_pk_add_f32 v[62:63], v[90:91], v[62:63]
	v_add3_u32 v49, 16, v203, v208
	v_mfma_f32_32x32x16_bf16 v[16:31], v[92:95], v[84:87], v[16:31]
	v_exp_f32_e32 v84, v117
	v_exp_f32_e32 v85, v118
	v_exp_f32_e32 v86, v119
	v_exp_f32_e32 v87, v122
	v_pk_add_f32 v[62:63], v[102:103], v[62:63]
	s_nop 0
	v_pk_add_f32 v[62:63], v[84:85], v[62:63]
	s_waitcnt lgkmcnt(1)
	v_mfma_f32_32x32x16_bf16 v[64:79], v[80:83], v[54:57], v[64:79]
	v_add_f32_e64 v62, v112, v62
	v_add_f32_e64 v63, v113, v63
	v_add_f32_e64 v62, v86, v62
	v_add_f32_e64 v63, v87, v63
	v_add_f32_e64 v62, v114, v62
	v_add_f32_e64 v63, v115, v63
	v_pk_add_f32 v[62:63], v[88:89], v[62:63]
	s_waitcnt lgkmcnt(0)
	v_mfma_f32_32x32x16_bf16 v[0:15], v[58:61], v[54:57], v[0:15]
	v_cvt_pk_bf16_f32 v54, v90, v91
	v_cvt_pk_bf16_f32 v55, v84, v85
	v_cvt_pk_bf16_f32 v56, v86, v87
	v_cvt_pk_bf16_f32 v57, v88, v89
	v_pk_add_f32 v[62:63], v[62:63], v[62:63] op_sel_hi:[0,1]
	v_mov_b32_e32 v62, v161
	v_pk_add_f32 v[222:223], v[104:105], v[62:63]
	v_mfma_f32_32x32x16_bf16 v[32:47], v[80:83], v[54:57], v[32:47]
	v_add_f32_e64 v80, -v222, neg(0)
	v_add_f32_e64 v81, -v223, neg(0)
	v_mov_b32_e32 v62, v48
	v_mov_b32_e32 v81, v80
	v_mov_b32_e32 v82, v80
	v_mov_b32_e32 v83, v80
	v_mov_b32_e32 v84, v80
	v_mov_b32_e32 v85, v80
	v_mfma_f32_32x32x16_bf16 v[16:31], v[58:61], v[54:57], v[16:31]
	v_add_u32_e32 v54, 0x6a00, v49
	v_add_u32_e32 v49, v49, v120
	s_waitcnt vmcnt(1)
	ds_write_b128 v49, v[194:197] offset:17920
	s_waitcnt vmcnt(0)
	ds_write2_b64 v54, v[198:199], v[200:201] offset1:1
	v_mov_b32_e32 v86, v80
	v_mov_b32_e32 v87, v80
	v_mov_b32_e32 v88, v80
	v_mov_b32_e32 v89, v80
	v_mov_b32_e32 v90, v80
	v_mov_b32_e32 v91, v80
	v_mov_b32_e32 v92, v80
	v_mov_b32_e32 v93, v80
	v_mov_b32_e32 v94, v80
	v_mov_b32_e32 v95, v80
	v_mov_b32_e32 v49, v48
	v_mov_b32_e32 v54, v48
	v_mov_b32_e32 v55, v48
	v_mov_b32_e32 v56, v48
	v_mov_b32_e32 v57, v48
	v_mov_b32_e32 v58, v48
	v_mov_b32_e32 v59, v48
	v_mov_b32_e32 v60, v48
	v_mov_b32_e32 v61, v48
	v_mov_b32_e32 v63, v48
	s_waitcnt lgkmcnt(0)
	s_barrier
	s_cmp_lt_u32 s11, 3
	s_cselect_b64 s[2:3], -1, 0
	s_cmp_gt_u32 s11, 2
	s_cbranch_scc1 .LBB0_350
